# grid barrier: L1 invalidate issued before polling / behind the top arrival (all other waves parked, polls bypass L1) so it overlaps the wait
# speedup vs baseline: 1.0393x; 1.0113x over previous
.LBB0_237:
	s_or_b64 exec, exec, s[20:21]
	v_cvt_f32_u32_e32 v4, v2
	s_waitcnt vmcnt(0)
	v_readfirstlane_b32 s3, v3
	v_sub_u32_e32 v3, 0, v2
	v_rcp_iflag_f32_e32 v4, v4
	v_add_u32_e32 v5, s3, v1
	v_mul_f32_e32 v4, 0x4f7ffffe, v4
	v_cvt_u32_f32_e32 v4, v4
	v_mul_lo_u32 v1, v3, v4
	v_mul_hi_u32 v1, v4, v1
	v_add_u32_e32 v1, v4, v1
	v_mul_hi_u32 v1, v5, v1
	v_mul_lo_u32 v3, v1, v2
	v_sub_u32_e32 v3, v5, v3
	v_add_u32_e32 v4, 1, v1
	v_cmp_ge_u32_e32 vcc, v3, v2
	s_nop 1
	v_cndmask_b32_e32 v1, v1, v4, vcc
	v_sub_u32_e32 v4, v3, v2
	v_cndmask_b32_e32 v3, v3, v4, vcc
	v_add_u32_e32 v4, 1, v1
	v_cmp_ge_u32_e32 vcc, v3, v2
	v_add_u32_e32 v3, 1, v5
	s_nop 0
	v_cndmask_b32_e32 v1, v1, v4, vcc
	v_mul_lo_u32 v4, v2, v1
	v_add_u32_e32 v2, v4, v2
	v_cmp_ne_u32_e32 vcc, v3, v2
	s_and_saveexec_b64 s[6:7], vcc
	s_xor_b64 s[6:7], exec, s[6:7]
	s_cbranch_execz .LBB0_251
	buffer_inv sc1
	s_waitcnt lgkmcnt(0)
	v_add_u32_e32 v3, 1, v1
	v_mul_lo_u32 v3, v3, v0
	v_mov_b32_e32 v0, 0x67000
	global_load_dword v0, v0, s[28:29] offset:1024 sc1
	s_add_u32 s48, s28, 0x67400
	s_addc_u32 s49, s29, 0
	s_waitcnt vmcnt(0)
	v_cmp_lt_u32_e32 vcc, v0, v3
	s_and_saveexec_b64 s[20:21], vcc
	s_cbranch_execz .LBB0_250
	s_add_u32 s46, s28, 0x64200
	s_addc_u32 s47, s29, 0
	s_mov_b32 s3, 1
	s_mov_b64 s[50:51], 0
	v_mov_b32_e32 v0, 0
	s_branch .LBB0_241

.LBB0_250:
	s_or_b64 exec, exec, s[20:21]
	s_waitcnt vmcnt(0)
	s_waitcnt vmcnt(0)

.LBB0_254:
	s_or_b64 exec, exec, s[20:21]
	buffer_inv sc1
	v_cvt_f32_u32_e32 v3, v0
	s_waitcnt vmcnt(0)
	v_readfirstlane_b32 s3, v2
	s_add_u32 s20, s28, 0x67500
	s_addc_u32 s21, s29, 0
	v_rcp_iflag_f32_e32 v3, v3
	v_add_u32_e32 v1, s3, v1
	v_add_u32_e32 v4, 1, v1
	s_mov_b64 s[46:47], -1
	v_mul_f32_e32 v2, 0x4f7ffffe, v3
	v_cvt_u32_f32_e32 v2, v2
	v_sub_u32_e32 v3, 0, v0
	v_mul_lo_u32 v3, v3, v2
	v_mul_hi_u32 v3, v2, v3
	v_add_u32_e32 v2, v2, v3
	v_mul_hi_u32 v2, v1, v2
	v_mul_lo_u32 v3, v2, v0
	v_sub_u32_e32 v1, v1, v3
	v_add_u32_e32 v5, 1, v2
	v_cmp_ge_u32_e32 vcc, v1, v0
	v_sub_u32_e32 v3, v1, v0
	s_nop 0
	v_cndmask_b32_e32 v2, v2, v5, vcc
	v_cndmask_b32_e32 v1, v1, v3, vcc
	v_add_u32_e32 v3, 1, v2
	v_cmp_ge_u32_e32 vcc, v1, v0
	s_nop 1
	v_cndmask_b32_e32 v2, v2, v3, vcc
	v_mul_lo_u32 v1, v0, v2
	v_add_u32_e32 v0, v1, v0
	v_cmp_ne_u32_e32 vcc, v4, v0
	v_mov_b32_e32 v5, v0
	v_mov_b64_e32 v[0:1], s[20:21]
	s_and_saveexec_b64 s[6:7], vcc
	s_cbranch_execz .LBB0_266
	v_mov_b32_e32 v0, 0
	global_load_dword v1, v0, s[20:21] offset:-256 sc1
	s_mov_b64 s[50:51], 0
	s_waitcnt vmcnt(0)
	v_cmp_lt_u32_e32 vcc, v1, v5
	s_and_saveexec_b64 s[48:49], vcc
	s_cbranch_execz .LBB0_265
	s_add_u32 s46, s28, 0x64200
	s_addc_u32 s47, s29, 0
	s_mov_b32 s3, 1
	s_branch .LBB0_258

.LBB0_268:
	s_or_b64 exec, exec, s[6:7]
	s_mov_b64 s[6:7], exec
	v_mbcnt_lo_u32_b32 v0, s6, 0
	v_mbcnt_hi_u32_b32 v0, s7, v0
	v_cmp_eq_u32_e32 vcc, 0, v0
	s_waitcnt vmcnt(0)
	s_and_saveexec_b64 s[20:21], vcc
	s_cbranch_execz .LBB0_270
	s_bcnt1_i32_b64 s3, s[6:7]
	v_mov_b32_e32 v0, 0x2000
	v_mov_b32_e32 v1, s3
	global_atomic_add v0, v1, s[4:5] offset:1024

.LBB0_364:
	s_or_b64 exec, exec, s[8:9]
	v_cvt_f32_u32_e32 v4, v2
	s_waitcnt vmcnt(0)
	v_readfirstlane_b32 s3, v3
	v_sub_u32_e32 v3, 0, v2
	v_rcp_iflag_f32_e32 v4, v4
	v_add_u32_e32 v5, s3, v1
	v_mul_f32_e32 v4, 0x4f7ffffe, v4
	v_cvt_u32_f32_e32 v4, v4
	v_mul_lo_u32 v1, v3, v4
	v_mul_hi_u32 v1, v4, v1
	v_add_u32_e32 v1, v4, v1
	v_mul_hi_u32 v1, v5, v1
	v_mul_lo_u32 v3, v1, v2
	v_sub_u32_e32 v3, v5, v3
	v_add_u32_e32 v4, 1, v1
	v_cmp_ge_u32_e32 vcc, v3, v2
	s_nop 1
	v_cndmask_b32_e32 v1, v1, v4, vcc
	v_sub_u32_e32 v4, v3, v2
	v_cndmask_b32_e32 v3, v3, v4, vcc
	v_add_u32_e32 v4, 1, v1
	v_cmp_ge_u32_e32 vcc, v3, v2
	v_add_u32_e32 v3, 1, v5
	s_nop 0
	v_cndmask_b32_e32 v1, v1, v4, vcc
	v_mul_lo_u32 v4, v2, v1
	v_add_u32_e32 v2, v4, v2
	v_cmp_ne_u32_e32 vcc, v3, v2
	s_and_saveexec_b64 s[6:7], vcc
	s_xor_b64 s[6:7], exec, s[6:7]
	s_cbranch_execz .LBB0_378
	buffer_inv sc1
	s_waitcnt lgkmcnt(0)
	v_add_u32_e32 v3, 1, v1
	v_mul_lo_u32 v3, v3, v0
	v_mov_b32_e32 v0, 0x67000
	global_load_dword v0, v0, s[28:29] offset:1024 sc1
	s_add_u32 s12, s28, 0x67400
	s_addc_u32 s13, s29, 0
	s_waitcnt vmcnt(0)
	v_cmp_lt_u32_e32 vcc, v0, v3
	s_and_saveexec_b64 s[8:9], vcc
	s_cbranch_execz .LBB0_377
	s_add_u32 s10, s28, 0x64200
	s_addc_u32 s11, s29, 0
	s_mov_b32 s3, 1
	s_mov_b64 s[14:15], 0
	v_mov_b32_e32 v0, 0
	s_branch .LBB0_368

.LBB0_377:
	s_or_b64 exec, exec, s[8:9]
	s_waitcnt vmcnt(0)
	s_waitcnt vmcnt(0)

.LBB0_381:
	s_or_b64 exec, exec, s[8:9]
	buffer_inv sc1
	v_cvt_f32_u32_e32 v3, v0
	s_waitcnt vmcnt(0)
	v_readfirstlane_b32 s3, v2
	s_add_u32 s8, s28, 0x67500
	s_addc_u32 s9, s29, 0
	v_rcp_iflag_f32_e32 v3, v3
	v_add_u32_e32 v1, s3, v1
	v_add_u32_e32 v4, 1, v1
	s_mov_b64 s[10:11], -1
	v_mul_f32_e32 v2, 0x4f7ffffe, v3
	v_cvt_u32_f32_e32 v2, v2
	v_sub_u32_e32 v3, 0, v0
	v_mul_lo_u32 v3, v3, v2
	v_mul_hi_u32 v3, v2, v3
	v_add_u32_e32 v2, v2, v3
	v_mul_hi_u32 v2, v1, v2
	v_mul_lo_u32 v3, v2, v0
	v_sub_u32_e32 v1, v1, v3
	v_add_u32_e32 v5, 1, v2
	v_cmp_ge_u32_e32 vcc, v1, v0
	v_sub_u32_e32 v3, v1, v0
	s_nop 0
	v_cndmask_b32_e32 v2, v2, v5, vcc
	v_cndmask_b32_e32 v1, v1, v3, vcc
	v_add_u32_e32 v3, 1, v2
	v_cmp_ge_u32_e32 vcc, v1, v0
	s_nop 1
	v_cndmask_b32_e32 v2, v2, v3, vcc
	v_mul_lo_u32 v1, v0, v2
	v_add_u32_e32 v0, v1, v0
	v_cmp_ne_u32_e32 vcc, v4, v0
	v_mov_b32_e32 v5, v0
	v_mov_b64_e32 v[0:1], s[8:9]
	s_and_saveexec_b64 s[6:7], vcc
	s_cbranch_execz .LBB0_395
	v_mov_b32_e32 v0, 0
	global_load_dword v1, v0, s[8:9] offset:-256 sc1
	s_mov_b64 s[14:15], 0
	s_waitcnt vmcnt(0)
	v_cmp_lt_u32_e32 vcc, v1, v5
	s_and_saveexec_b64 s[12:13], vcc
	s_cbranch_execz .LBB0_394
	s_add_u32 s10, s28, 0x64200
	s_addc_u32 s11, s29, 0
	s_mov_b32 s3, 1
	s_branch .LBB0_385

.LBB0_397:
	s_or_b64 exec, exec, s[6:7]
	s_mov_b64 s[6:7], exec
	v_mbcnt_lo_u32_b32 v0, s6, 0
	v_mbcnt_hi_u32_b32 v0, s7, v0
	v_cmp_eq_u32_e32 vcc, 0, v0
	s_waitcnt vmcnt(0)
	s_and_saveexec_b64 s[8:9], vcc
	s_cbranch_execz .LBB0_399
	s_bcnt1_i32_b64 s3, s[6:7]
	v_mov_b32_e32 v0, 0x2000
	v_mov_b32_e32 v1, s3
	global_atomic_add v0, v1, s[4:5] offset:1024

.LBB0_660:
	s_or_b64 exec, exec, s[8:9]
	v_cvt_f32_u32_e32 v4, v2
	s_waitcnt vmcnt(0)
	v_readfirstlane_b32 s3, v3
	v_sub_u32_e32 v3, 0, v2
	v_rcp_iflag_f32_e32 v4, v4
	v_add_u32_e32 v5, s3, v1
	v_mul_f32_e32 v4, 0x4f7ffffe, v4
	v_cvt_u32_f32_e32 v4, v4
	v_mul_lo_u32 v1, v3, v4
	v_mul_hi_u32 v1, v4, v1
	v_add_u32_e32 v1, v4, v1
	v_mul_hi_u32 v1, v5, v1
	v_mul_lo_u32 v3, v1, v2
	v_sub_u32_e32 v3, v5, v3
	v_add_u32_e32 v4, 1, v1
	v_cmp_ge_u32_e32 vcc, v3, v2
	s_nop 1
	v_cndmask_b32_e32 v1, v1, v4, vcc
	v_sub_u32_e32 v4, v3, v2
	v_cndmask_b32_e32 v3, v3, v4, vcc
	v_add_u32_e32 v4, 1, v1
	v_cmp_ge_u32_e32 vcc, v3, v2
	v_add_u32_e32 v3, 1, v5
	s_nop 0
	v_cndmask_b32_e32 v1, v1, v4, vcc
	v_mul_lo_u32 v4, v2, v1
	v_add_u32_e32 v2, v4, v2
	v_cmp_ne_u32_e32 vcc, v3, v2
	s_and_saveexec_b64 s[6:7], vcc
	s_xor_b64 s[6:7], exec, s[6:7]
	s_cbranch_execz .LBB0_674
	buffer_inv sc1
	s_waitcnt lgkmcnt(0)
	v_add_u32_e32 v3, 1, v1
	v_mul_lo_u32 v3, v3, v0
	v_mov_b32_e32 v0, 0x67000
	global_load_dword v0, v0, s[28:29] offset:1024 sc1
	s_add_u32 s12, s28, 0x67400
	s_addc_u32 s13, s29, 0
	s_waitcnt vmcnt(0)
	v_cmp_lt_u32_e32 vcc, v0, v3
	s_and_saveexec_b64 s[8:9], vcc
	s_cbranch_execz .LBB0_673
	s_add_u32 s10, s28, 0x64200
	s_addc_u32 s11, s29, 0
	s_mov_b32 s3, 1
	s_mov_b64 s[60:61], 0
	v_mov_b32_e32 v0, 0
	s_branch .LBB0_664

.LBB0_677:
	s_or_b64 exec, exec, s[8:9]
	buffer_inv sc1
	v_cvt_f32_u32_e32 v3, v0
	s_waitcnt vmcnt(0)
	v_readfirstlane_b32 s3, v2
	s_add_u32 s8, s28, 0x67500
	s_addc_u32 s9, s29, 0
	v_rcp_iflag_f32_e32 v3, v3
	v_add_u32_e32 v1, s3, v1
	v_add_u32_e32 v4, 1, v1
	s_mov_b64 s[10:11], -1
	v_mul_f32_e32 v2, 0x4f7ffffe, v3
	v_cvt_u32_f32_e32 v2, v2
	v_sub_u32_e32 v3, 0, v0
	v_mul_lo_u32 v3, v3, v2
	v_mul_hi_u32 v3, v2, v3
	v_add_u32_e32 v2, v2, v3
	v_mul_hi_u32 v2, v1, v2
	v_mul_lo_u32 v3, v2, v0
	v_sub_u32_e32 v1, v1, v3
	v_add_u32_e32 v5, 1, v2
	v_cmp_ge_u32_e32 vcc, v1, v0
	v_sub_u32_e32 v3, v1, v0
	s_nop 0
	v_cndmask_b32_e32 v2, v2, v5, vcc
	v_cndmask_b32_e32 v1, v1, v3, vcc
	v_add_u32_e32 v3, 1, v2
	v_cmp_ge_u32_e32 vcc, v1, v0
	s_nop 1
	v_cndmask_b32_e32 v2, v2, v3, vcc
	v_mul_lo_u32 v1, v0, v2
	v_add_u32_e32 v0, v1, v0
	v_cmp_ne_u32_e32 vcc, v4, v0
	v_mov_b32_e32 v5, v0
	v_mov_b64_e32 v[0:1], s[8:9]
	s_and_saveexec_b64 s[6:7], vcc
	s_cbranch_execz .LBB0_689
	v_mov_b32_e32 v0, 0
	global_load_dword v1, v0, s[8:9] offset:-256 sc1
	s_mov_b64 s[60:61], 0
	s_waitcnt vmcnt(0)
	v_cmp_lt_u32_e32 vcc, v1, v5
	s_and_saveexec_b64 s[12:13], vcc
	s_cbranch_execz .LBB0_688
	s_add_u32 s10, s28, 0x64200
	s_addc_u32 s11, s29, 0
	s_mov_b32 s3, 1
	s_branch .LBB0_681

.LBB0_715:
	s_or_b64 exec, exec, s[8:9]
	v_cvt_f32_u32_e32 v4, v2
	s_waitcnt vmcnt(0)
	v_readfirstlane_b32 s3, v3
	v_sub_u32_e32 v3, 0, v2
	v_rcp_iflag_f32_e32 v4, v4
	v_add_u32_e32 v5, s3, v1
	v_mul_f32_e32 v4, 0x4f7ffffe, v4
	v_cvt_u32_f32_e32 v4, v4
	v_mul_lo_u32 v1, v3, v4
	v_mul_hi_u32 v1, v4, v1
	v_add_u32_e32 v1, v4, v1
	v_mul_hi_u32 v1, v5, v1
	v_mul_lo_u32 v3, v1, v2
	v_sub_u32_e32 v3, v5, v3
	v_add_u32_e32 v4, 1, v1
	v_cmp_ge_u32_e32 vcc, v3, v2
	s_nop 1
	v_cndmask_b32_e32 v1, v1, v4, vcc
	v_sub_u32_e32 v4, v3, v2
	v_cndmask_b32_e32 v3, v3, v4, vcc
	v_add_u32_e32 v4, 1, v1
	v_cmp_ge_u32_e32 vcc, v3, v2
	v_add_u32_e32 v3, 1, v5
	s_nop 0
	v_cndmask_b32_e32 v1, v1, v4, vcc
	v_mul_lo_u32 v4, v2, v1
	v_add_u32_e32 v2, v4, v2
	v_cmp_ne_u32_e32 vcc, v3, v2
	s_and_saveexec_b64 s[6:7], vcc
	s_xor_b64 s[6:7], exec, s[6:7]
	s_cbranch_execz .LBB0_729
	buffer_inv sc1
	s_waitcnt lgkmcnt(0)
	v_add_u32_e32 v3, 1, v1
	v_mul_lo_u32 v3, v3, v0
	v_mov_b32_e32 v0, 0x67000
	global_load_dword v0, v0, s[28:29] offset:1024 sc1
	s_add_u32 s12, s28, 0x67400
	s_addc_u32 s13, s29, 0
	s_waitcnt vmcnt(0)
	v_cmp_lt_u32_e32 vcc, v0, v3
	s_and_saveexec_b64 s[8:9], vcc
	s_cbranch_execz .LBB0_728
	s_add_u32 s10, s28, 0x64200
	s_addc_u32 s11, s29, 0
	s_mov_b32 s3, 1
	s_mov_b64 s[36:37], 0
	v_mov_b32_e32 v0, 0
	s_branch .LBB0_719

.LBB0_732:
	s_or_b64 exec, exec, s[8:9]
	buffer_inv sc1
	v_cvt_f32_u32_e32 v3, v0
	s_waitcnt vmcnt(0)
	v_readfirstlane_b32 s3, v2
	s_add_u32 s8, s28, 0x67500
	s_addc_u32 s9, s29, 0
	v_rcp_iflag_f32_e32 v3, v3
	v_add_u32_e32 v1, s3, v1
	v_add_u32_e32 v4, 1, v1
	s_mov_b64 s[10:11], -1
	v_mul_f32_e32 v2, 0x4f7ffffe, v3
	v_cvt_u32_f32_e32 v2, v2
	v_sub_u32_e32 v3, 0, v0
	v_mul_lo_u32 v3, v3, v2
	v_mul_hi_u32 v3, v2, v3
	v_add_u32_e32 v2, v2, v3
	v_mul_hi_u32 v2, v1, v2
	v_mul_lo_u32 v3, v2, v0
	v_sub_u32_e32 v1, v1, v3
	v_add_u32_e32 v5, 1, v2
	v_cmp_ge_u32_e32 vcc, v1, v0
	v_sub_u32_e32 v3, v1, v0
	s_nop 0
	v_cndmask_b32_e32 v2, v2, v5, vcc
	v_cndmask_b32_e32 v1, v1, v3, vcc
	v_add_u32_e32 v3, 1, v2
	v_cmp_ge_u32_e32 vcc, v1, v0
	s_nop 1
	v_cndmask_b32_e32 v2, v2, v3, vcc
	v_mul_lo_u32 v1, v0, v2
	v_add_u32_e32 v0, v1, v0
	v_cmp_ne_u32_e32 vcc, v4, v0
	v_mov_b32_e32 v5, v0
	v_mov_b64_e32 v[0:1], s[8:9]
	s_and_saveexec_b64 s[6:7], vcc
	s_cbranch_execz .LBB0_744
	v_mov_b32_e32 v0, 0
	global_load_dword v1, v0, s[8:9] offset:-256 sc1
	s_mov_b64 s[36:37], 0
	s_waitcnt vmcnt(0)
	v_cmp_lt_u32_e32 vcc, v1, v5
	s_and_saveexec_b64 s[12:13], vcc
	s_cbranch_execz .LBB0_743
	s_add_u32 s10, s28, 0x64200
	s_addc_u32 s11, s29, 0
	s_mov_b32 s3, 1
	s_branch .LBB0_736

.LBB0_986:
	s_or_b64 exec, exec, s[10:11]
	v_cvt_f32_u32_e32 v4, v2
	s_waitcnt vmcnt(0)
	v_readfirstlane_b32 s3, v3
	v_sub_u32_e32 v3, 0, v2
	v_rcp_iflag_f32_e32 v4, v4
	v_add_u32_e32 v5, s3, v1
	v_mul_f32_e32 v4, 0x4f7ffffe, v4
	v_cvt_u32_f32_e32 v4, v4
	v_mul_lo_u32 v1, v3, v4
	v_mul_hi_u32 v1, v4, v1
	v_add_u32_e32 v1, v4, v1
	v_mul_hi_u32 v1, v5, v1
	v_mul_lo_u32 v3, v1, v2
	v_sub_u32_e32 v3, v5, v3
	v_add_u32_e32 v4, 1, v1
	v_cmp_ge_u32_e32 vcc, v3, v2
	s_nop 1
	v_cndmask_b32_e32 v1, v1, v4, vcc
	v_sub_u32_e32 v4, v3, v2
	v_cndmask_b32_e32 v3, v3, v4, vcc
	v_add_u32_e32 v4, 1, v1
	v_cmp_ge_u32_e32 vcc, v3, v2
	v_add_u32_e32 v3, 1, v5
	s_nop 0
	v_cndmask_b32_e32 v1, v1, v4, vcc
	v_mul_lo_u32 v4, v2, v1
	v_add_u32_e32 v2, v4, v2
	v_cmp_ne_u32_e32 vcc, v3, v2
	s_and_saveexec_b64 s[8:9], vcc
	s_xor_b64 s[8:9], exec, s[8:9]
	s_cbranch_execz .LBB0_1000
	buffer_inv sc1
	s_waitcnt lgkmcnt(0)
	v_add_u32_e32 v3, 1, v1
	v_mul_lo_u32 v3, v3, v0
	v_mov_b32_e32 v0, 0x67000
	global_load_dword v0, v0, s[28:29] offset:1024 sc1
	s_add_u32 s14, s28, 0x67400
	s_addc_u32 s15, s29, 0
	s_waitcnt vmcnt(0)
	v_cmp_lt_u32_e32 vcc, v0, v3
	s_and_saveexec_b64 s[10:11], vcc
	s_cbranch_execz .LBB0_999
	s_add_u32 s12, s28, 0x64200
	s_addc_u32 s13, s29, 0
	s_mov_b32 s3, 1
	s_mov_b64 s[40:41], 0
	v_mov_b32_e32 v0, 0
	s_branch .LBB0_990

.LBB0_999:
	s_or_b64 exec, exec, s[10:11]
	s_waitcnt vmcnt(0)
	s_waitcnt vmcnt(0)

.LBB0_1003:
	s_or_b64 exec, exec, s[10:11]
	buffer_inv sc1
	v_cvt_f32_u32_e32 v3, v0
	s_waitcnt vmcnt(0)
	v_readfirstlane_b32 s3, v2
	s_add_u32 s10, s28, 0x67500
	s_addc_u32 s11, s29, 0
	v_rcp_iflag_f32_e32 v3, v3
	v_add_u32_e32 v1, s3, v1
	v_add_u32_e32 v4, 1, v1
	s_mov_b64 s[12:13], -1
	v_mul_f32_e32 v2, 0x4f7ffffe, v3
	v_cvt_u32_f32_e32 v2, v2
	v_sub_u32_e32 v3, 0, v0
	v_mul_lo_u32 v3, v3, v2
	v_mul_hi_u32 v3, v2, v3
	v_add_u32_e32 v2, v2, v3
	v_mul_hi_u32 v2, v1, v2
	v_mul_lo_u32 v3, v2, v0
	v_sub_u32_e32 v1, v1, v3
	v_add_u32_e32 v5, 1, v2
	v_cmp_ge_u32_e32 vcc, v1, v0
	v_sub_u32_e32 v3, v1, v0
	s_nop 0
	v_cndmask_b32_e32 v2, v2, v5, vcc
	v_cndmask_b32_e32 v1, v1, v3, vcc
	v_add_u32_e32 v3, 1, v2
	v_cmp_ge_u32_e32 vcc, v1, v0
	s_nop 1
	v_cndmask_b32_e32 v2, v2, v3, vcc
	v_mul_lo_u32 v1, v0, v2
	v_add_u32_e32 v0, v1, v0
	v_cmp_ne_u32_e32 vcc, v4, v0
	v_mov_b32_e32 v5, v0
	v_mov_b64_e32 v[0:1], s[10:11]
	s_and_saveexec_b64 s[8:9], vcc
	s_cbranch_execz .LBB0_1015
	v_mov_b32_e32 v0, 0
	global_load_dword v1, v0, s[10:11] offset:-256 sc1
	s_mov_b64 s[40:41], 0
	s_waitcnt vmcnt(0)
	v_cmp_lt_u32_e32 vcc, v1, v5
	s_and_saveexec_b64 s[14:15], vcc
	s_cbranch_execz .LBB0_1014
	s_add_u32 s12, s28, 0x64200
	s_addc_u32 s13, s29, 0
	s_mov_b32 s3, 1
	s_branch .LBB0_1007

.LBB0_1017:
	s_or_b64 exec, exec, s[8:9]
	s_mov_b64 s[8:9], exec
	v_mbcnt_lo_u32_b32 v0, s8, 0
	v_mbcnt_hi_u32_b32 v0, s9, v0
	v_cmp_eq_u32_e32 vcc, 0, v0
	s_waitcnt vmcnt(0)
	s_and_saveexec_b64 s[10:11], vcc
	s_cbranch_execz .LBB0_1019
	s_bcnt1_i32_b64 s3, s[8:9]
	v_mov_b32_e32 v0, 0x2000
	v_mov_b32_e32 v1, s3
	global_atomic_add v0, v1, s[6:7] offset:1024

.LBB0_1041:
	s_or_b64 exec, exec, s[10:11]
	v_cvt_f32_u32_e32 v4, v2
	s_waitcnt vmcnt(0)
	v_readfirstlane_b32 s3, v3
	v_sub_u32_e32 v3, 0, v2
	v_rcp_iflag_f32_e32 v4, v4
	v_add_u32_e32 v5, s3, v1
	v_mul_f32_e32 v4, 0x4f7ffffe, v4
	v_cvt_u32_f32_e32 v4, v4
	v_mul_lo_u32 v1, v3, v4
	v_mul_hi_u32 v1, v4, v1
	v_add_u32_e32 v1, v4, v1
	v_mul_hi_u32 v1, v5, v1
	v_mul_lo_u32 v3, v1, v2
	v_sub_u32_e32 v3, v5, v3
	v_add_u32_e32 v4, 1, v1
	v_cmp_ge_u32_e32 vcc, v3, v2
	s_nop 1
	v_cndmask_b32_e32 v1, v1, v4, vcc
	v_sub_u32_e32 v4, v3, v2
	v_cndmask_b32_e32 v3, v3, v4, vcc
	v_add_u32_e32 v4, 1, v1
	v_cmp_ge_u32_e32 vcc, v3, v2
	v_add_u32_e32 v3, 1, v5
	s_nop 0
	v_cndmask_b32_e32 v1, v1, v4, vcc
	v_mul_lo_u32 v4, v2, v1
	v_add_u32_e32 v2, v4, v2
	v_cmp_ne_u32_e32 vcc, v3, v2
	s_and_saveexec_b64 s[8:9], vcc
	s_xor_b64 s[8:9], exec, s[8:9]
	s_cbranch_execz .LBB0_1055
	buffer_inv sc1
	s_waitcnt lgkmcnt(0)
	v_add_u32_e32 v3, 1, v1
	v_mul_lo_u32 v3, v3, v0
	v_mov_b32_e32 v0, 0x67000
	global_load_dword v0, v0, s[28:29] offset:1024 sc1
	s_add_u32 s14, s28, 0x67400
	s_addc_u32 s15, s29, 0
	s_waitcnt vmcnt(0)
	v_cmp_lt_u32_e32 vcc, v0, v3
	s_and_saveexec_b64 s[10:11], vcc
	s_cbranch_execz .LBB0_1054
	s_add_u32 s12, s28, 0x64200
	s_addc_u32 s13, s29, 0
	s_mov_b32 s3, 1
	s_mov_b64 s[16:17], 0
	v_mov_b32_e32 v0, 0
	s_branch .LBB0_1045

.LBB0_1058:
	s_or_b64 exec, exec, s[10:11]
	buffer_inv sc1
	v_cvt_f32_u32_e32 v3, v0
	s_waitcnt vmcnt(0)
	v_readfirstlane_b32 s3, v2
	s_add_u32 s10, s28, 0x67500
	s_addc_u32 s11, s29, 0
	v_rcp_iflag_f32_e32 v3, v3
	v_add_u32_e32 v1, s3, v1
	v_add_u32_e32 v4, 1, v1
	s_mov_b64 s[12:13], -1
	v_mul_f32_e32 v2, 0x4f7ffffe, v3
	v_cvt_u32_f32_e32 v2, v2
	v_sub_u32_e32 v3, 0, v0
	v_mul_lo_u32 v3, v3, v2
	v_mul_hi_u32 v3, v2, v3
	v_add_u32_e32 v2, v2, v3
	v_mul_hi_u32 v2, v1, v2
	v_mul_lo_u32 v3, v2, v0
	v_sub_u32_e32 v1, v1, v3
	v_add_u32_e32 v5, 1, v2
	v_cmp_ge_u32_e32 vcc, v1, v0
	v_sub_u32_e32 v3, v1, v0
	s_nop 0
	v_cndmask_b32_e32 v2, v2, v5, vcc
	v_cndmask_b32_e32 v1, v1, v3, vcc
	v_add_u32_e32 v3, 1, v2
	v_cmp_ge_u32_e32 vcc, v1, v0
	s_nop 1
	v_cndmask_b32_e32 v2, v2, v3, vcc
	v_mul_lo_u32 v1, v0, v2
	v_add_u32_e32 v0, v1, v0
	v_cmp_ne_u32_e32 vcc, v4, v0
	v_mov_b32_e32 v5, v0
	v_mov_b64_e32 v[0:1], s[10:11]
	s_and_saveexec_b64 s[8:9], vcc
	s_cbranch_execz .LBB0_1070
	v_mov_b32_e32 v0, 0
	global_load_dword v1, v0, s[10:11] offset:-256 sc1
	s_mov_b64 s[16:17], 0
	s_waitcnt vmcnt(0)
	v_cmp_lt_u32_e32 vcc, v1, v5
	s_and_saveexec_b64 s[14:15], vcc
	s_cbranch_execz .LBB0_1069
	s_add_u32 s12, s28, 0x64200
	s_addc_u32 s13, s29, 0
	s_mov_b32 s3, 1
	s_branch .LBB0_1062
